# P0a w_in transposes: workgroup takes 8 consecutive k blocks of one n block (32 rows x 1 KB contiguous writes), on p0map
# speedup vs baseline: 1.0061x; 1.0061x over previous
.LBB0_77:
	s_andn2_b64 vcc, exec, s[6:7]
	s_cbranch_vccnz .LBB0_11
	s_lshr_b32 s62, s4, 3
	s_mul_hi_i32 s6, s62, 0x43b3d5b
	s_ashr_i32 s6, s6, 2
	s_waitcnt lgkmcnt(0)
	s_load_dwordx2 s[10:11], s[12:13], 0x40
	s_mul_i32 s7, s6, 0xf2
	s_sub_i32 s7, s62, s7
	s_and_b32 s63, s4, 7
	s_lshl_b32 s6, s6, 3
	s_add_i32 s6, s6, s63
	s_lshl_b32 s8, s6, 6
	s_lshl_b32 s6, s7, 5
	s_cmpk_gt_i32 s7, 0xbf
	s_mov_b64 s[26:27], -1
	v_or_b32_e32 v3, s8, v1
	v_or_b32_e32 v2, s8, v38
	s_cbranch_scc0 .LBB0_82
	s_mov_b32 s7, s17
	s_lshl_b64 s[26:27], s[6:7], 2
	s_waitcnt lgkmcnt(0)
	s_add_u32 s26, s10, s26
	s_addc_u32 s27, s11, s27
	v_mov_b32_e32 v61, v35
	v_lshl_add_u64 v[4:5], s[26:27], 0, v[60:61]
	s_mov_b32 s7, 1
	s_mov_b32 s9, 0
	s_mov_b32 s16, 32
